# v42 plus 64-byte alignment of the compressed-branch loop heads and the top-k bit loop (code placement)
# baseline (speedup 1.0000x reference)
; #define AF_WAITV(n) asm volatile("s_waitcnt vmcnt(" #n ")" ::: "memory")
; #define AF_BAR() do { __builtin_amdgcn_s_barrier(); asm volatile("" ::: "memory"); } while (0)
; __device__ __forceinline__ void attn_fast(const Ptrs& P, LAS unsigned char* lds, int G, int bid) {
;     ...
; #pragma unroll 1
;             for (int T = 0; T < ntc; ++T) {
;                 if (T + 1 < ntc) AF_WAITV(2); else AF_WAITV(0);
;                 AF_BAR();
;                 if (T + 2 < ntc) AF_ISSUE((T + 2) % 3, KC, VC, 128, 64 * (T + 2), false);
;                 af_qk<true, true>(lds + (T % 3) * 32768, kl, qf, s);
; #pragma unroll
;                 for (int ct = 0; ct < 2; ++ct) {
;                     if (1024 * T + 1039 > 64 * qb) af_maskraw(s[ct], 1024 * T + 31, 16, fq, tq[ct], NEGBIG);
;                     const float mn = fmaxf(m[ct], af_rawmax(s[ct]) * SC); const float al = __builtin_amdgcn_exp2f(m[ct] - mn); m[ct] = mn; float ps = 0.f;
; #pragma unroll
;                     for (int kt = 0; kt < 4; ++kt)
; #pragma unroll
;                         for (int jj = 0; jj < 4; ++jj) ps += __builtin_amdgcn_exp2f(__builtin_fmaf(s[ct][kt][jj], SC, -mn));
;                     l[ct] = l[ct] * al + ps; }
.LBB0_522:
	s_waitcnt vmcnt(0)
	s_mov_b64 s[52:53], 0
	.p2alignl 6, 3212836864

; #define AF_WAITV(n) asm volatile("s_waitcnt vmcnt(" #n ")" ::: "memory")
; #define AF_BAR() do { __builtin_amdgcn_s_barrier(); asm volatile("" ::: "memory"); } while (0)
; __device__ __forceinline__ void attn_fast(const Ptrs& P, LAS unsigned char* lds, int G, int bid) {
;     ...
; #pragma unroll 1
;             for (int T = 0; T < ntc; ++T) {
;                 if (T + 1 < ntc) AF_WAITV(4); else AF_WAITV(0);
;                 AF_BAR();
;                 if (T + 2 < ntc) AF_ISSUE((T + 2) % 3, KC, VC, 128, 64 * (T + 2), true);
;                 af_qk<true, true>(lds + (T % 3) * 32768, kl, qf, s);
.LBB0_540:
	s_waitcnt vmcnt(0)
	s_mov_b64 s[6:7], 0
	.p2alignl 6, 3212836864

; #define LAS __attribute__((address_space(3)))
; __device__ __forceinline__ void attn_fast(const Ptrs& P, LAS unsigned char* lds, int G, int bid) {
;     ...
;             for (int ql = 0; ql < 8; ql += 2) {
;                 LAS float* rowa = IMP + ql * 132; LAS float* rowb = rowa + 132;
;                 float a0, a1, b0, b1;
;                 { const int j = lane; const bool valid = j <= qb, forced = (j == 0) || (j == qb) || (j == qb - 1); const float bonus = forced ? 1.0e4f : 0.f;
;                   const float va = rowa[j], vb = rowb[j]; a0 = valid ? va + bonus : -1.f; b0 = valid ? vb + bonus : -1.f; rowa[j] = a0; rowb[j] = b0; }
;                 { const int j = lane + 64; const bool valid = j <= qb, forced = (j == 0) || (j == qb) || (j == qb - 1); const float bonus = forced ? 1.0e4f : 0.f;
;                   const float va = rowa[j], vb = rowb[j]; a1 = valid ? va + bonus : -1.f; b1 = valid ? vb + bonus : -1.f; rowa[j] = a1; rowb[j] = b1; }
.Ltk_radix:
	s_mul_i32 s6, s3, 0x210
	s_add_i32 s6, s66, s6
	v_lshl_add_u32 v40, v172, 2, s6
	ds_read2st64_b32 v[4:5], v40 offset1:1
	ds_read2_b32 v[38:39], v40 offset0:132 offset1:196
	s_waitcnt lgkmcnt(0)
	v_add_f32_e32 v4, v210, v4
	v_add_f32_e32 v38, v210, v38
	v_add_f32_e32 v5, v211, v5
	v_add_f32_e32 v39, v211, v39
	v_add_u32_e32 v4, 1, v4
	v_add_u32_e32 v38, 1, v38
	v_add_u32_e32 v5, 1, v5
	v_add_u32_e32 v39, 1, v39
	v_cndmask_b32_e64 v4, 0, v4, s[44:45]
	v_cndmask_b32_e64 v38, 0, v38, s[44:45]
	v_cndmask_b32_e64 v5, 0, v5, s[46:47]
	v_cndmask_b32_e64 v39, 0, v39, s[46:47]
	s_mov_b32 s16, 0
	s_mov_b32 s17, 0
	s_mov_b32 s22, 0x40000000
	.p2alignl 6, 3212836864
